# code placement: peeled first-iteration heads also pinned to 64-byte boundaries
# baseline (speedup 1.0000x reference)
.LBB7_325:
	s_add_u32 s34, s62, s77
	s_addc_u32 s35, s63, s52
	s_add_u32 s36, s62, s30
	s_addc_u32 s37, s63, s31
	s_andn2_b64 vcc, exec, s[14:15]
	s_cbranch_vccnz .LBB7_337
	s_and_b64 s[42:43], s[6:7], exec
	s_cselect_b32 s81, s35, s39
	s_cselect_b32 s82, s34, s38
	s_cselect_b32 s83, s37, s41
	s_cselect_b32 s84, s36, s40
	s_add_u32 s38, s38, 0x40080
	s_addc_u32 s39, s39, 0
	s_add_u32 s85, s40, 0x100
	s_addc_u32 s86, s41, 0
	s_mov_b32 s40, 0
	s_waitcnt vmcnt(0)
	.p2align	6

.Lswi_nobar:
	.p2align	6

.LBB7_432:
	s_add_u32 s52, s70, s48
	s_addc_u32 s53, s71, s49
	s_add_u32 s54, s5, s50
	s_addc_u32 s55, s22, s51
	s_andn2_b64 vcc, exec, s[14:15]
	s_cbranch_vccnz .LBB7_435
	s_and_b64 s[16:17], s[44:45], exec
	s_cselect_b32 s20, s53, s19
	s_cselect_b32 s86, s52, s18
	s_cselect_b32 s87, s55, s9
	s_cselect_b32 s37, s54, s8
	s_add_u32 s29, s8, 0x10000
	s_addc_u32 s74, s9, 0
	s_add_u32 s16, s18, 0xc000
	s_addc_u32 s17, s19, 0
	s_mov_b32 s72, 0
	.p2align	6

.LBB7_521:
	s_add_u32 s52, s68, s18
	s_addc_u32 s53, s69, s19
	v_readlane_b32 s13, v254, 48
	s_add_u32 s54, s13, s50
	v_readlane_b32 s13, v254, 49
	s_addc_u32 s55, s13, s51
	s_andn2_b64 vcc, exec, s[8:9]
	s_cbranch_vccnz .LBB7_609
	s_and_b64 s[38:39], s[40:41], exec
	s_cselect_b32 s13, s53, s17
	s_cselect_b32 s15, s52, s16
	s_cselect_b32 s38, s55, s43
	s_cselect_b32 s39, s54, s42
	s_add_u32 s16, s16, 0x40080
	s_addc_u32 s17, s17, 0
	s_add_u32 s48, s42, 0x100
	s_addc_u32 s49, s43, 0
	s_mov_b32 s42, 0
	.p2align	6

.LBB7_674:
	s_add_u32 s16, s70, s12
	s_addc_u32 s17, s71, s13
	v_readlane_b32 s18, v254, 24
	s_add_u32 s18, s18, s14
	v_readlane_b32 s19, v254, 25
	s_addc_u32 s19, s19, s15
	s_andn2_b64 vcc, exec, s[8:9]
	s_cbranch_vccnz .LBB7_682
	s_and_b64 s[48:49], s[40:41], exec
	s_cselect_b32 s56, s17, s43
	s_cselect_b32 s57, s16, s42
	s_cselect_b32 s72, s19, s45
	s_cselect_b32 s73, s18, s44
	s_add_u32 s84, s44, 0x100
	s_addc_u32 s85, s45, 0
	s_mov_b32 s37, 0
	.p2align	6

.LBB7_884:
	s_cmp_eq_u32 s29, 0
	s_cselect_b32 s38, s3, s29
	s_add_u32 s14, s70, s8
	s_addc_u32 s15, s71, s9
	v_readlane_b32 s18, v252, 38
	s_add_u32 s18, s18, s12
	v_readlane_b32 s19, v252, 40
	s_addc_u32 s19, s19, s13
	s_cmp_lt_i32 s38, 1
	s_cbranch_scc1 .LBB7_892
	s_and_b64 s[44:45], s[40:41], exec
	s_cselect_b32 s39, s15, s17
	s_cselect_b32 s54, s14, s16
	s_cselect_b32 s55, s19, s43
	s_cselect_b32 s56, s18, s42
	s_add_i32 s57, s38, -2
	s_add_u32 s72, s42, 0x100
	s_addc_u32 s73, s43, 0
	s_mov_b32 s44, 0
	.p2align	6

.LBB7_961:
	s_add_u32 s18, s46, s12
	s_addc_u32 s19, s47, s13
	v_readlane_b32 s29, v254, 56
	s_add_u32 s44, s29, s14
	v_readlane_b32 s29, v254, 57
	s_addc_u32 s45, s29, s15
	s_andn2_b64 vcc, exec, s[8:9]
	s_cbranch_vccnz .LBB7_1033
	s_and_b64 s[38:39], s[40:41], exec
	s_cselect_b32 s38, s19, s17
	s_cselect_b32 s39, s18, s16
	s_cselect_b32 s56, s45, s43
	s_cselect_b32 s57, s44, s42
	s_add_u32 s72, s42, 0x100
	s_addc_u32 s73, s43, 0
	s_mov_b32 s48, 0
	s_waitcnt vmcnt(0)
	.p2align	6

.LBB7_1102:
	s_add_u32 s54, s64, s50
	s_addc_u32 s55, s65, s51
	v_readlane_b32 s12, v250, 0
	s_add_u32 s12, s12, s52
	v_readlane_b32 s13, v250, 1
	s_addc_u32 s13, s13, s53
	s_andn2_b64 vcc, exec, s[8:9]
	s_cbranch_vccnz .LBB7_1105
	s_and_b64 s[28:29], s[44:45], exec
	s_cselect_b32 s19, s55, s15
	s_cselect_b32 s20, s54, s14
	s_cselect_b32 s28, s13, s17
	s_cselect_b32 s29, s12, s16
	s_add_u32 s37, s16, 0x100
	s_addc_u32 s49, s17, 0
	s_add_u32 vcc_lo, s14, 0x40080
	s_addc_u32 vcc_hi, s15, 0
	s_mov_b32 s72, 0
	.p2align	6

.LBB7_1194:
	s_add_u32 s48, s68, s18
	s_addc_u32 s49, s69, s19
	v_readlane_b32 s13, v254, 32
	s_add_u32 s50, s13, s44
	v_readlane_b32 s13, v254, 33
	s_addc_u32 s51, s13, s45
	s_andn2_b64 vcc, exec, s[8:9]
	s_cbranch_vccnz .LBB7_1202
	s_and_b64 s[28:29], s[40:41], exec
	s_cselect_b32 s13, s49, s17
	s_cselect_b32 s15, s48, s16
	s_cselect_b32 s28, s51, s43
	s_cselect_b32 s39, s50, s42
	s_add_u32 s16, s16, 0x40080
	s_addc_u32 s17, s17, 0
	s_add_u32 s56, s42, 0x100
	s_addc_u32 s57, s43, 0
	s_mov_b32 s42, 0
	.p2align	6

.LBB7_1217:
	s_add_u32 s48, s94, s18
	s_addc_u32 s49, s95, s19
	s_add_u32 s50, s77, s44
	v_readlane_b32 s10, v250, 9
	s_addc_u32 s51, s10, s45
	s_andn2_b64 vcc, exec, s[8:9]
	s_cbranch_vccnz .LBB7_1257
	s_and_b64 s[28:29], s[42:43], exec
	s_cselect_b32 s10, s49, s17
	s_cselect_b32 s13, s48, s16
	s_cselect_b32 s15, s51, s53
	s_cselect_b32 s28, s50, s52
	s_add_u32 s16, s16, 0x40080
	s_addc_u32 s17, s17, 0
	s_add_u32 s38, s52, 0x100
	s_addc_u32 s39, s53, 0
	s_mov_b32 s52, 0
	.p2align	6

.LBB7_1272:
	s_add_u32 s42, s64, s16
	s_addc_u32 s43, s65, s17
	v_readlane_b32 s13, v254, 40
	s_add_u32 s44, s13, s18
	v_readlane_b32 s13, v254, 41
	s_addc_u32 s45, s13, s19
	s_andn2_b64 vcc, exec, s[8:9]
	s_cbranch_vccnz .LBB7_1280
	s_and_b64 s[52:53], s[40:41], exec
	s_cselect_b32 s13, s43, s49
	s_cselect_b32 s15, s42, s48
	s_cselect_b32 s54, s45, s51
	s_cselect_b32 s55, s44, s50
	s_add_u32 s48, s48, 0x40080
	s_addc_u32 s49, s49, 0
	s_add_u32 s56, s50, 0x100
	s_addc_u32 s57, s51, 0
	s_mov_b32 s50, 0
	.p2align	6

.LBB7_1349:
	s_add_u32 s54, s94, s50
	s_addc_u32 s55, s95, s51
	v_readlane_b32 s16, v250, 18
	s_add_u32 s16, s16, s52
	v_readlane_b32 s17, v250, 19
	s_addc_u32 s17, s17, s53
	s_andn2_b64 vcc, exec, s[8:9]
	s_cbranch_vccnz .LBB7_1352
	s_and_b64 s[28:29], s[44:45], exec
	s_cselect_b32 s19, s55, s15
	s_cselect_b32 s20, s54, s14
	s_cselect_b32 s28, s17, s13
	s_cselect_b32 s29, s16, s12
	s_add_u32 s37, s12, 0x100
	s_addc_u32 s49, s13, 0
	s_add_u32 vcc_lo, s14, 0x40080
	s_addc_u32 vcc_hi, s15, 0
	s_mov_b32 s72, 0
	.p2align	6
